# qg image builder: row-group loads pipelined 8 deep with counted waits (on top of inverse v2)
# speedup vs baseline: 1.0072x; 1.0072x over previous
; __device__ __forceinline__ unsigned pk2(float a, float b) { return pg8::cvt_pk_bf16(a, b); }
; __device__ __forceinline__ void unpack8(const u32x4 w, float (&f)[8]) { f[0] = bf_lo(w.x); f[1] = bf_hi(w.x); f[2] = bf_lo(w.y); f[3] = bf_hi(w.y); f[4] = bf_lo(w.z); f[5] = bf_hi(w.z); f[6] = bf_lo(w.w); f[7] = bf_hi(w.w); }
; __device__ __forceinline__ void phase_prep(const Args& a, PG8_LAS unsigned char* lds) {
;     ...
; #pragma unroll 4
;             for (int k = 0; k < 16; ++k) { const int pidx = lane + 64 * k, i = pidx >> 4, pc = pidx & 15, aa = pc & 3, c32 = (pc >> 2) * 32;
;                 float f[8]; unpack8(*(const u32x4*)(qbase + (size_t)i * 512 + pc * 8), f); const float e = sE[i];
;                 u32x2 lo, hi; lo.x = pk2(f[0] * e, f[1] * e); lo.y = pk2(f[2] * e, f[3] * e); hi.x = pk2(f[4] * e, f[5] * e); hi.y = pk2(f[6] * e, f[7] * e);
;                 *(u32x2*)(qgp + i * 128 + c32 + 8 * ((2 * aa) & 3) + 4 * (aa >> 1)) = lo;
;                 *(u32x2*)(qgp + i * 128 + c32 + 8 * ((2 * aa + 1) & 3) + 4 * (aa >> 1)) = hi; }
.LBB0_296:
	v_lshl_add_u64 v[40:41], s[16:17], 0, v[32:33]
	v_add_co_u32_e32 v40, vcc, 0x10001000, v40
	s_nop 1
	v_addc_co_u32_e32 v41, vcc, 0, v41, vcc
	v_lshl_add_u64 v[42:43], s[16:17], 0, v[34:35]
	s_mov_b64 s[24:25], 0x2000
	s_mov_b64 s[26:27], 0x1000
	ds_read_b32 v84, v206
	ds_read_b32 v85, v206 offset:16
	ds_read_b32 v86, v206 offset:32
	ds_read_b32 v87, v206 offset:48
	ds_read_b32 v88, v206 offset:64
	ds_read_b32 v89, v206 offset:80
	ds_read_b32 v90, v206 offset:96
	ds_read_b32 v91, v206 offset:112
	ds_read_b32 v92, v206 offset:128
	ds_read_b32 v93, v206 offset:144
	ds_read_b32 v94, v206 offset:160
	ds_read_b32 v95, v206 offset:176
	ds_read_b32 v44, v206 offset:192
	ds_read_b32 v45, v206 offset:208
	ds_read_b32 v46, v206 offset:224
	ds_read_b32 v47, v206 offset:240
	global_load_dwordx4 v[52:55], v[40:41], off offset:-4096
	global_load_dwordx4 v[56:59], v[40:41], off
	v_lshl_add_u64 v[40:41], v[40:41], 0, s[24:25]
	global_load_dwordx4 v[60:63], v[40:41], off offset:-4096
	global_load_dwordx4 v[64:67], v[40:41], off
	v_lshl_add_u64 v[40:41], v[40:41], 0, s[24:25]
	global_load_dwordx4 v[68:71], v[40:41], off offset:-4096
	global_load_dwordx4 v[72:75], v[40:41], off
	v_lshl_add_u64 v[40:41], v[40:41], 0, s[24:25]
	global_load_dwordx4 v[76:79], v[40:41], off offset:-4096
	global_load_dwordx4 v[80:83], v[40:41], off
	v_lshl_add_u64 v[40:41], v[40:41], 0, s[24:25]
	s_waitcnt lgkmcnt(0)
	s_waitcnt vmcnt(7)
	v_lshlrev_b32_e32 v48, 16, v52
	v_and_b32_e32 v52, 0xffff0000, v52
	v_lshlrev_b32_e32 v49, 16, v53
	v_and_b32_e32 v53, 0xffff0000, v53
	v_lshlrev_b32_e32 v50, 16, v54
	v_and_b32_e32 v54, 0xffff0000, v54
	v_lshlrev_b32_e32 v51, 16, v55
	v_and_b32_e32 v55, 0xffff0000, v55
	v_mul_f32_e32 v52, v84, v52
	v_mul_f32_e32 v48, v84, v48
	v_mul_f32_e32 v53, v84, v53
	v_mul_f32_e32 v49, v84, v49
	v_mul_f32_e32 v54, v84, v54
	v_mul_f32_e32 v50, v84, v50
	v_mul_f32_e32 v55, v84, v55
	v_mul_f32_e32 v51, v84, v51
	v_cvt_pk_bf16_f32 v52, v48, v52
	v_cvt_pk_bf16_f32 v53, v49, v53
	v_cvt_pk_bf16_f32 v54, v50, v54
	v_cvt_pk_bf16_f32 v55, v51, v55
	global_store_dwordx2 v[42:43], v[52:53], off offset:-2048
	global_store_dwordx2 v[42:43], v[54:55], off offset:-2032
	s_nop 0
	global_load_dwordx4 v[52:55], v[40:41], off offset:-4096
	s_waitcnt vmcnt(9)
	v_lshlrev_b32_e32 v48, 16, v56
	v_and_b32_e32 v56, 0xffff0000, v56
	v_lshlrev_b32_e32 v49, 16, v57
	v_and_b32_e32 v57, 0xffff0000, v57
	v_lshlrev_b32_e32 v50, 16, v58
	v_and_b32_e32 v58, 0xffff0000, v58
	v_lshlrev_b32_e32 v51, 16, v59
	v_and_b32_e32 v59, 0xffff0000, v59
	v_mul_f32_e32 v56, v85, v56
	v_mul_f32_e32 v48, v85, v48
	v_mul_f32_e32 v57, v85, v57
	v_mul_f32_e32 v49, v85, v49
	v_mul_f32_e32 v58, v85, v58
	v_mul_f32_e32 v50, v85, v50
	v_mul_f32_e32 v59, v85, v59
	v_mul_f32_e32 v51, v85, v51
	v_cvt_pk_bf16_f32 v56, v48, v56
	v_cvt_pk_bf16_f32 v57, v49, v57
	v_cvt_pk_bf16_f32 v58, v50, v58
	v_cvt_pk_bf16_f32 v59, v51, v59
	global_store_dwordx2 v[42:43], v[56:57], off offset:-1024
	global_store_dwordx2 v[42:43], v[58:59], off offset:-1008
	s_nop 0
	global_load_dwordx4 v[56:59], v[40:41], off
	v_lshl_add_u64 v[40:41], v[40:41], 0, s[24:25]
	s_waitcnt vmcnt(11)
	v_lshlrev_b32_e32 v48, 16, v60
	v_and_b32_e32 v60, 0xffff0000, v60
	v_lshlrev_b32_e32 v49, 16, v61
	v_and_b32_e32 v61, 0xffff0000, v61
	v_lshlrev_b32_e32 v50, 16, v62
	v_and_b32_e32 v62, 0xffff0000, v62
	v_lshlrev_b32_e32 v51, 16, v63
	v_and_b32_e32 v63, 0xffff0000, v63
	v_mul_f32_e32 v60, v86, v60
	v_mul_f32_e32 v48, v86, v48
	v_mul_f32_e32 v61, v86, v61
	v_mul_f32_e32 v49, v86, v49
	v_mul_f32_e32 v62, v86, v62
	v_mul_f32_e32 v50, v86, v50
	v_mul_f32_e32 v63, v86, v63
	v_mul_f32_e32 v51, v86, v51
	v_cvt_pk_bf16_f32 v60, v48, v60
	v_cvt_pk_bf16_f32 v61, v49, v61
	v_cvt_pk_bf16_f32 v62, v50, v62
	v_cvt_pk_bf16_f32 v63, v51, v63
	global_store_dwordx2 v[42:43], v[60:61], off
	global_store_dwordx2 v[42:43], v[62:63], off offset:16
	s_nop 0
	global_load_dwordx4 v[60:63], v[40:41], off offset:-4096
	s_waitcnt vmcnt(13)
	v_lshlrev_b32_e32 v48, 16, v64
	v_and_b32_e32 v64, 0xffff0000, v64
	v_lshlrev_b32_e32 v49, 16, v65
	v_and_b32_e32 v65, 0xffff0000, v65
	v_lshlrev_b32_e32 v50, 16, v66
	v_and_b32_e32 v66, 0xffff0000, v66
	v_lshlrev_b32_e32 v51, 16, v67
	v_and_b32_e32 v67, 0xffff0000, v67
	v_mul_f32_e32 v64, v87, v64
	v_mul_f32_e32 v48, v87, v48
	v_mul_f32_e32 v65, v87, v65
	v_mul_f32_e32 v49, v87, v49
	v_mul_f32_e32 v66, v87, v66
	v_mul_f32_e32 v50, v87, v50
	v_mul_f32_e32 v67, v87, v67
	v_mul_f32_e32 v51, v87, v51
	v_cvt_pk_bf16_f32 v64, v48, v64
	v_cvt_pk_bf16_f32 v65, v49, v65
	v_cvt_pk_bf16_f32 v66, v50, v66
	v_cvt_pk_bf16_f32 v67, v51, v67
	global_store_dwordx2 v[42:43], v[64:65], off offset:1024
	global_store_dwordx2 v[42:43], v[66:67], off offset:1040
	v_lshl_add_u64 v[42:43], v[42:43], 0, s[26:27]
	s_nop 0
	global_load_dwordx4 v[64:67], v[40:41], off
	v_lshl_add_u64 v[40:41], v[40:41], 0, s[24:25]
	s_waitcnt vmcnt(15)
	v_lshlrev_b32_e32 v48, 16, v68
	v_and_b32_e32 v68, 0xffff0000, v68
	v_lshlrev_b32_e32 v49, 16, v69
	v_and_b32_e32 v69, 0xffff0000, v69
	v_lshlrev_b32_e32 v50, 16, v70
	v_and_b32_e32 v70, 0xffff0000, v70
	v_lshlrev_b32_e32 v51, 16, v71
	v_and_b32_e32 v71, 0xffff0000, v71
	v_mul_f32_e32 v68, v88, v68
	v_mul_f32_e32 v48, v88, v48
	v_mul_f32_e32 v69, v88, v69
	v_mul_f32_e32 v49, v88, v49
	v_mul_f32_e32 v70, v88, v70
	v_mul_f32_e32 v50, v88, v50
	v_mul_f32_e32 v71, v88, v71
	v_mul_f32_e32 v51, v88, v51
	v_cvt_pk_bf16_f32 v68, v48, v68
	v_cvt_pk_bf16_f32 v69, v49, v69
	v_cvt_pk_bf16_f32 v70, v50, v70
	v_cvt_pk_bf16_f32 v71, v51, v71
	global_store_dwordx2 v[42:43], v[68:69], off offset:-2048
	global_store_dwordx2 v[42:43], v[70:71], off offset:-2032
	s_nop 0
	global_load_dwordx4 v[68:71], v[40:41], off offset:-4096
	s_waitcnt vmcnt(17)
; __device__ __forceinline__ unsigned pk2(float a, float b) { return pg8::cvt_pk_bf16(a, b); }
; __device__ __forceinline__ void unpack8(const u32x4 w, float (&f)[8]) { f[0] = bf_lo(w.x); f[1] = bf_hi(w.x); f[2] = bf_lo(w.y); f[3] = bf_hi(w.y); f[4] = bf_lo(w.z); f[5] = bf_hi(w.z); f[6] = bf_lo(w.w); f[7] = bf_hi(w.w); }
; __device__ __forceinline__ void phase_prep(const Args& a, PG8_LAS unsigned char* lds) {
;     ...
; #pragma unroll 4
;             for (int k = 0; k < 16; ++k) { const int pidx = lane + 64 * k, i = pidx >> 4, pc = pidx & 15, aa = pc & 3, c32 = (pc >> 2) * 32;
;                 float f[8]; unpack8(*(const u32x4*)(qbase + (size_t)i * 512 + pc * 8), f); const float e = sE[i];
;                 u32x2 lo, hi; lo.x = pk2(f[0] * e, f[1] * e); lo.y = pk2(f[2] * e, f[3] * e); hi.x = pk2(f[4] * e, f[5] * e); hi.y = pk2(f[6] * e, f[7] * e);
;                 *(u32x2*)(qgp + i * 128 + c32 + 8 * ((2 * aa) & 3) + 4 * (aa >> 1)) = lo;
;                 *(u32x2*)(qgp + i * 128 + c32 + 8 * ((2 * aa + 1) & 3) + 4 * (aa >> 1)) = hi; }
	v_lshlrev_b32_e32 v48, 16, v72
	v_and_b32_e32 v72, 0xffff0000, v72
	v_lshlrev_b32_e32 v49, 16, v73
	v_and_b32_e32 v73, 0xffff0000, v73
	v_lshlrev_b32_e32 v50, 16, v74
	v_and_b32_e32 v74, 0xffff0000, v74
	v_lshlrev_b32_e32 v51, 16, v75
	v_and_b32_e32 v75, 0xffff0000, v75
	v_mul_f32_e32 v72, v89, v72
	v_mul_f32_e32 v48, v89, v48
	v_mul_f32_e32 v73, v89, v73
	v_mul_f32_e32 v49, v89, v49
	v_mul_f32_e32 v74, v89, v74
	v_mul_f32_e32 v50, v89, v50
	v_mul_f32_e32 v75, v89, v75
	v_mul_f32_e32 v51, v89, v51
	v_cvt_pk_bf16_f32 v72, v48, v72
	v_cvt_pk_bf16_f32 v73, v49, v73
	v_cvt_pk_bf16_f32 v74, v50, v74
	v_cvt_pk_bf16_f32 v75, v51, v75
	global_store_dwordx2 v[42:43], v[72:73], off offset:-1024
	global_store_dwordx2 v[42:43], v[74:75], off offset:-1008
	s_nop 0
	global_load_dwordx4 v[72:75], v[40:41], off
	v_lshl_add_u64 v[40:41], v[40:41], 0, s[24:25]
	s_waitcnt vmcnt(19)
	v_lshlrev_b32_e32 v48, 16, v76
	v_and_b32_e32 v76, 0xffff0000, v76
	v_lshlrev_b32_e32 v49, 16, v77
	v_and_b32_e32 v77, 0xffff0000, v77
	v_lshlrev_b32_e32 v50, 16, v78
	v_and_b32_e32 v78, 0xffff0000, v78
	v_lshlrev_b32_e32 v51, 16, v79
	v_and_b32_e32 v79, 0xffff0000, v79
	v_mul_f32_e32 v76, v90, v76
	v_mul_f32_e32 v48, v90, v48
	v_mul_f32_e32 v77, v90, v77
	v_mul_f32_e32 v49, v90, v49
	v_mul_f32_e32 v78, v90, v78
	v_mul_f32_e32 v50, v90, v50
	v_mul_f32_e32 v79, v90, v79
	v_mul_f32_e32 v51, v90, v51
	v_cvt_pk_bf16_f32 v76, v48, v76
	v_cvt_pk_bf16_f32 v77, v49, v77
	v_cvt_pk_bf16_f32 v78, v50, v78
	v_cvt_pk_bf16_f32 v79, v51, v79
	global_store_dwordx2 v[42:43], v[76:77], off
	global_store_dwordx2 v[42:43], v[78:79], off offset:16
	s_nop 0
	global_load_dwordx4 v[76:79], v[40:41], off offset:-4096
	s_waitcnt vmcnt(21)
	v_lshlrev_b32_e32 v48, 16, v80
	v_and_b32_e32 v80, 0xffff0000, v80
	v_lshlrev_b32_e32 v49, 16, v81
	v_and_b32_e32 v81, 0xffff0000, v81
	v_lshlrev_b32_e32 v50, 16, v82
	v_and_b32_e32 v82, 0xffff0000, v82
	v_lshlrev_b32_e32 v51, 16, v83
	v_and_b32_e32 v83, 0xffff0000, v83
	v_mul_f32_e32 v80, v91, v80
	v_mul_f32_e32 v48, v91, v48
	v_mul_f32_e32 v81, v91, v81
	v_mul_f32_e32 v49, v91, v49
	v_mul_f32_e32 v82, v91, v82
	v_mul_f32_e32 v50, v91, v50
	v_mul_f32_e32 v83, v91, v83
	v_mul_f32_e32 v51, v91, v51
	v_cvt_pk_bf16_f32 v80, v48, v80
	v_cvt_pk_bf16_f32 v81, v49, v81
	v_cvt_pk_bf16_f32 v82, v50, v82
	v_cvt_pk_bf16_f32 v83, v51, v83
	global_store_dwordx2 v[42:43], v[80:81], off offset:1024
	global_store_dwordx2 v[42:43], v[82:83], off offset:1040
	v_lshl_add_u64 v[42:43], v[42:43], 0, s[26:27]
	s_nop 0
	global_load_dwordx4 v[80:83], v[40:41], off
	v_lshl_add_u64 v[40:41], v[40:41], 0, s[24:25]
	s_waitcnt vmcnt(21)
	v_lshlrev_b32_e32 v48, 16, v52
	v_and_b32_e32 v52, 0xffff0000, v52
	v_lshlrev_b32_e32 v49, 16, v53
	v_and_b32_e32 v53, 0xffff0000, v53
	v_lshlrev_b32_e32 v50, 16, v54
	v_and_b32_e32 v54, 0xffff0000, v54
	v_lshlrev_b32_e32 v51, 16, v55
	v_and_b32_e32 v55, 0xffff0000, v55
	v_mul_f32_e32 v52, v92, v52
	v_mul_f32_e32 v48, v92, v48
	v_mul_f32_e32 v53, v92, v53
	v_mul_f32_e32 v49, v92, v49
	v_mul_f32_e32 v54, v92, v54
	v_mul_f32_e32 v50, v92, v50
	v_mul_f32_e32 v55, v92, v55
	v_mul_f32_e32 v51, v92, v51
	v_cvt_pk_bf16_f32 v52, v48, v52
	v_cvt_pk_bf16_f32 v53, v49, v53
	v_cvt_pk_bf16_f32 v54, v50, v54
	v_cvt_pk_bf16_f32 v55, v51, v55
	global_store_dwordx2 v[42:43], v[52:53], off offset:-2048
	global_store_dwordx2 v[42:43], v[54:55], off offset:-2032
	s_waitcnt vmcnt(20)
	v_lshlrev_b32_e32 v48, 16, v56
	v_and_b32_e32 v56, 0xffff0000, v56
	v_lshlrev_b32_e32 v49, 16, v57
	v_and_b32_e32 v57, 0xffff0000, v57
	v_lshlrev_b32_e32 v50, 16, v58
	v_and_b32_e32 v58, 0xffff0000, v58
	v_lshlrev_b32_e32 v51, 16, v59
	v_and_b32_e32 v59, 0xffff0000, v59
	v_mul_f32_e32 v56, v93, v56
	v_mul_f32_e32 v48, v93, v48
	v_mul_f32_e32 v57, v93, v57
	v_mul_f32_e32 v49, v93, v49
	v_mul_f32_e32 v58, v93, v58
	v_mul_f32_e32 v50, v93, v50
	v_mul_f32_e32 v59, v93, v59
	v_mul_f32_e32 v51, v93, v51
	v_cvt_pk_bf16_f32 v56, v48, v56
	v_cvt_pk_bf16_f32 v57, v49, v57
	v_cvt_pk_bf16_f32 v58, v50, v58
	v_cvt_pk_bf16_f32 v59, v51, v59
	global_store_dwordx2 v[42:43], v[56:57], off offset:-1024
	global_store_dwordx2 v[42:43], v[58:59], off offset:-1008
	s_waitcnt vmcnt(19)
; __device__ __forceinline__ unsigned pk2(float a, float b) { return pg8::cvt_pk_bf16(a, b); }
; __device__ __forceinline__ void unpack8(const u32x4 w, float (&f)[8]) { f[0] = bf_lo(w.x); f[1] = bf_hi(w.x); f[2] = bf_lo(w.y); f[3] = bf_hi(w.y); f[4] = bf_lo(w.z); f[5] = bf_hi(w.z); f[6] = bf_lo(w.w); f[7] = bf_hi(w.w); }
; __device__ __forceinline__ void phase_prep(const Args& a, PG8_LAS unsigned char* lds) {
;     ...
; #pragma unroll 4
;             for (int k = 0; k < 16; ++k) { const int pidx = lane + 64 * k, i = pidx >> 4, pc = pidx & 15, aa = pc & 3, c32 = (pc >> 2) * 32;
;                 float f[8]; unpack8(*(const u32x4*)(qbase + (size_t)i * 512 + pc * 8), f); const float e = sE[i];
;                 u32x2 lo, hi; lo.x = pk2(f[0] * e, f[1] * e); lo.y = pk2(f[2] * e, f[3] * e); hi.x = pk2(f[4] * e, f[5] * e); hi.y = pk2(f[6] * e, f[7] * e);
;                 *(u32x2*)(qgp + i * 128 + c32 + 8 * ((2 * aa) & 3) + 4 * (aa >> 1)) = lo;
;                 *(u32x2*)(qgp + i * 128 + c32 + 8 * ((2 * aa + 1) & 3) + 4 * (aa >> 1)) = hi; }
	v_lshlrev_b32_e32 v48, 16, v60
	v_and_b32_e32 v60, 0xffff0000, v60
	v_lshlrev_b32_e32 v49, 16, v61
	v_and_b32_e32 v61, 0xffff0000, v61
	v_lshlrev_b32_e32 v50, 16, v62
	v_and_b32_e32 v62, 0xffff0000, v62
	v_lshlrev_b32_e32 v51, 16, v63
	v_and_b32_e32 v63, 0xffff0000, v63
	v_mul_f32_e32 v60, v94, v60
	v_mul_f32_e32 v48, v94, v48
	v_mul_f32_e32 v61, v94, v61
	v_mul_f32_e32 v49, v94, v49
	v_mul_f32_e32 v62, v94, v62
	v_mul_f32_e32 v50, v94, v50
	v_mul_f32_e32 v63, v94, v63
	v_mul_f32_e32 v51, v94, v51
	v_cvt_pk_bf16_f32 v60, v48, v60
	v_cvt_pk_bf16_f32 v61, v49, v61
	v_cvt_pk_bf16_f32 v62, v50, v62
	v_cvt_pk_bf16_f32 v63, v51, v63
	global_store_dwordx2 v[42:43], v[60:61], off
	global_store_dwordx2 v[42:43], v[62:63], off offset:16
	s_waitcnt vmcnt(18)
	v_lshlrev_b32_e32 v48, 16, v64
	v_and_b32_e32 v64, 0xffff0000, v64
	v_lshlrev_b32_e32 v49, 16, v65
	v_and_b32_e32 v65, 0xffff0000, v65
	v_lshlrev_b32_e32 v50, 16, v66
	v_and_b32_e32 v66, 0xffff0000, v66
	v_lshlrev_b32_e32 v51, 16, v67
	v_and_b32_e32 v67, 0xffff0000, v67
	v_mul_f32_e32 v64, v95, v64
	v_mul_f32_e32 v48, v95, v48
	v_mul_f32_e32 v65, v95, v65
	v_mul_f32_e32 v49, v95, v49
	v_mul_f32_e32 v66, v95, v66
	v_mul_f32_e32 v50, v95, v50
	v_mul_f32_e32 v67, v95, v67
	v_mul_f32_e32 v51, v95, v51
	v_cvt_pk_bf16_f32 v64, v48, v64
	v_cvt_pk_bf16_f32 v65, v49, v65
	v_cvt_pk_bf16_f32 v66, v50, v66
	v_cvt_pk_bf16_f32 v67, v51, v67
	global_store_dwordx2 v[42:43], v[64:65], off offset:1024
	global_store_dwordx2 v[42:43], v[66:67], off offset:1040
	v_lshl_add_u64 v[42:43], v[42:43], 0, s[26:27]
	s_waitcnt vmcnt(17)
	v_lshlrev_b32_e32 v48, 16, v68
	v_and_b32_e32 v68, 0xffff0000, v68
	v_lshlrev_b32_e32 v49, 16, v69
	v_and_b32_e32 v69, 0xffff0000, v69
	v_lshlrev_b32_e32 v50, 16, v70
	v_and_b32_e32 v70, 0xffff0000, v70
	v_lshlrev_b32_e32 v51, 16, v71
	v_and_b32_e32 v71, 0xffff0000, v71
	v_mul_f32_e32 v68, v44, v68
	v_mul_f32_e32 v48, v44, v48
	v_mul_f32_e32 v69, v44, v69
	v_mul_f32_e32 v49, v44, v49
	v_mul_f32_e32 v70, v44, v70
	v_mul_f32_e32 v50, v44, v50
	v_mul_f32_e32 v71, v44, v71
	v_mul_f32_e32 v51, v44, v51
	v_cvt_pk_bf16_f32 v68, v48, v68
	v_cvt_pk_bf16_f32 v69, v49, v69
	v_cvt_pk_bf16_f32 v70, v50, v70
	v_cvt_pk_bf16_f32 v71, v51, v71
	global_store_dwordx2 v[42:43], v[68:69], off offset:-2048
	global_store_dwordx2 v[42:43], v[70:71], off offset:-2032
	s_waitcnt vmcnt(16)
	v_lshlrev_b32_e32 v48, 16, v72
	v_and_b32_e32 v72, 0xffff0000, v72
	v_lshlrev_b32_e32 v49, 16, v73
	v_and_b32_e32 v73, 0xffff0000, v73
	v_lshlrev_b32_e32 v50, 16, v74
	v_and_b32_e32 v74, 0xffff0000, v74
	v_lshlrev_b32_e32 v51, 16, v75
	v_and_b32_e32 v75, 0xffff0000, v75
	v_mul_f32_e32 v72, v45, v72
	v_mul_f32_e32 v48, v45, v48
	v_mul_f32_e32 v73, v45, v73
	v_mul_f32_e32 v49, v45, v49
	v_mul_f32_e32 v74, v45, v74
	v_mul_f32_e32 v50, v45, v50
	v_mul_f32_e32 v75, v45, v75
	v_mul_f32_e32 v51, v45, v51
	v_cvt_pk_bf16_f32 v72, v48, v72
	v_cvt_pk_bf16_f32 v73, v49, v73
	v_cvt_pk_bf16_f32 v74, v50, v74
	v_cvt_pk_bf16_f32 v75, v51, v75
	global_store_dwordx2 v[42:43], v[72:73], off offset:-1024
	global_store_dwordx2 v[42:43], v[74:75], off offset:-1008
	s_waitcnt vmcnt(15)
	v_lshlrev_b32_e32 v48, 16, v76
	v_and_b32_e32 v76, 0xffff0000, v76
	v_lshlrev_b32_e32 v49, 16, v77
	v_and_b32_e32 v77, 0xffff0000, v77
	v_lshlrev_b32_e32 v50, 16, v78
	v_and_b32_e32 v78, 0xffff0000, v78
	v_lshlrev_b32_e32 v51, 16, v79
	v_and_b32_e32 v79, 0xffff0000, v79
	v_mul_f32_e32 v76, v46, v76
	v_mul_f32_e32 v48, v46, v48
	v_mul_f32_e32 v77, v46, v77
	v_mul_f32_e32 v49, v46, v49
	v_mul_f32_e32 v78, v46, v78
	v_mul_f32_e32 v50, v46, v50
	v_mul_f32_e32 v79, v46, v79
	v_mul_f32_e32 v51, v46, v51
	v_cvt_pk_bf16_f32 v76, v48, v76
	v_cvt_pk_bf16_f32 v77, v49, v77
	v_cvt_pk_bf16_f32 v78, v50, v78
	v_cvt_pk_bf16_f32 v79, v51, v79
	global_store_dwordx2 v[42:43], v[76:77], off
	global_store_dwordx2 v[42:43], v[78:79], off offset:16
	s_waitcnt vmcnt(14)
	v_lshlrev_b32_e32 v48, 16, v80
	v_and_b32_e32 v80, 0xffff0000, v80
	v_lshlrev_b32_e32 v49, 16, v81
	v_and_b32_e32 v81, 0xffff0000, v81
	v_lshlrev_b32_e32 v50, 16, v82
	v_and_b32_e32 v82, 0xffff0000, v82
	v_lshlrev_b32_e32 v51, 16, v83
	v_and_b32_e32 v83, 0xffff0000, v83
	v_mul_f32_e32 v80, v47, v80
	v_mul_f32_e32 v48, v47, v48
	v_mul_f32_e32 v81, v47, v81
	v_mul_f32_e32 v49, v47, v49
	v_mul_f32_e32 v82, v47, v82
	v_mul_f32_e32 v50, v47, v50
	v_mul_f32_e32 v83, v47, v83
	v_mul_f32_e32 v51, v47, v51
	v_cvt_pk_bf16_f32 v80, v48, v80
	v_cvt_pk_bf16_f32 v81, v49, v81
	v_cvt_pk_bf16_f32 v82, v50, v82
	v_cvt_pk_bf16_f32 v83, v51, v83
	global_store_dwordx2 v[42:43], v[80:81], off offset:1024
	global_store_dwordx2 v[42:43], v[82:83], off offset:1040
